# filler transposes (w_glu/w_out, idle workgroups of the last in-projection round): dropped the stale vmcnt waits of the no-scale path that drained every tile load pair before the next was issued
# speedup vs baseline: 1.0147x; 1.0137x over previous
.LBB0_314:
	v_mov_b32_e32 v34, 1.0
	v_mov_b32_e32 v36, 1.0

.LBB0_317:
	v_mov_b32_e32 v38, 1.0
	v_mov_b32_e32 v40, 1.0

.LBB0_320:
	v_mov_b32_e32 v42, 1.0
	v_mov_b32_e32 v44, 1.0

.LBB0_323:
	v_mov_b32_e32 v48, 1.0
	v_mov_b32_e32 v46, 1.0
